# A/B of the static attention priority: s_setprio 1 on waves 0-3 instead of waves 4-7 (which half is the younger one)
# speedup vs baseline: 1.0111x; 1.0015x over previous
; template <int PH, bool RERUN>
; __device__ __forceinline__ void run_phase(unsigned char* shm, int vbid, int wave_s) {
;     unsigned z_ = 0u; int ws_ = wave_s; asm volatile("" : "+s"(z_)); asm volatile("" : "+s"(ws_));
;     int tid_ = (ws_ << 6) | (int)__builtin_amdgcn_mbcnt_hi(~0u, __builtin_amdgcn_mbcnt_lo(~0u, z_)), bid_ = __builtin_amdgcn_readfirstlane(vbid);
;     KParams pp_ = (KParams)__builtin_amdgcn_kernarg_segment_ptr();
;     asm volatile("" : "+v"(tid_)); asm volatile("" : "+s"(bid_)); asm volatile("" : "+s"(pp_));
;     Ctx c; c.p = pp_; c.ws = pp_->ws; c.bid = bid_; c.G = gridDim.x; c.tid = tid_; c.lane = tid_ & 63; c.wave = tid_ >> 6;
.LBB0_432:
	s_mov_b32 s2, 0
	s_waitcnt lgkmcnt(0)
	s_barrier
	s_mov_b32 s3, s33
	v_mbcnt_lo_u32_b32 v0, -1, s2
	v_mbcnt_hi_u32_b32 v0, -1, v0
	v_lshl_or_b32 v194, s3, 6, v0
	v_readfirstlane_b32 s35, v217
	s_cmp_ge_u32 s33, 4
	s_cbranch_scc1 .Lprio_skip_1
	s_setprio 1
